# conv tile placed between or after the attention units per pair type (slot table 0x5554, larger query block first for pairs 2,4,6) so conv tiles spread over the attention phase; w_out bf16 copy moved f
# speedup vs baseline: 1.0215x; 1.0105x over previous
.LBB0_341:
	s_cmp_lt_i32 s26, 4
	s_cselect_b64 s[6:7], -1, 0
	s_and_b64 s[30:31], s[6:7], s[4:5]
	s_andn2_b64 vcc, exec, s[30:31]
	s_cbranch_vccnz .LBB0_509
	v_and_b32_e32 v2, 63, v0
	s_cmpk_gt_i32 s2, 0xff
	s_mov_b64 s[34:35], s[24:25]
	v_mov_b32_e32 v254, v2
	s_cbranch_scc1 .LBB0_383
	s_lshr_b32 s32, s2, 3
	s_and_b32 s32, s32, 7
	s_lshl_b32 s32, s32, 1
	s_lshr_b32 s32, 0x5554, s32
	s_and_b32 s32, s32, 3
	s_lshl_b32 s32, s32, 4
	s_cmp_lt_u32 s32, 16
	s_cbranch_scc1 .Lconv_entry
	s_mov_b32 s11, 0
	s_mov_b64 s[4:5], exec
	s_branch .LBB0_385

.Lst_norm:
	s_ashr_i32 s6, s2, 31
	s_lshr_b32 s6, s6, 29
	s_add_i32 s6, s2, s6
	s_and_b32 s7, s6, -8
	s_ashr_i32 s5, s3, 3
	s_sub_i32 s66, s2, s7
	s_mul_i32 s5, s5, s66
	s_ashr_i32 s67, s6, 3
	s_and_b32 s4, s3, 7
	s_add_i32 s5, s5, s67
	s_cmpk_eq_i32 s3, 0x100
	s_cselect_b64 s[8:9], -1, 0
	s_cmpk_lg_i32 s3, 0x100
	s_mov_b64 s[14:15], s[24:25]
	s_cselect_b64 s[12:13], -1, 0
	s_add_u32 s68, s14, 0x5000000
	s_addc_u32 s69, s15, 0
	s_add_u32 s73, s14, 0x6000000
	s_addc_u32 s74, s15, 0
	s_add_u32 s75, s14, 0x7000000
	s_addc_u32 s76, s15, 0
	s_cmp_eq_u32 s4, 0
	s_cselect_b32 s77, s5, s2
	s_and_b32 s5, s77, 3
	s_and_b32 s6, s77, 2
	s_add_i32 s6, s6, s5
	s_and_b32 s4, s77, 4
	s_ashr_i32 s78, s77, 3
	s_sub_i32 s7, 13, s6
	s_xor_b32 s10, s5, 15
	s_sub_i32 s16, 13, s5
	s_add_i32 s17, s5, 2
	s_or_b32 s18, s5, 4
	s_cmp_lt_u32 s5, 2
	s_cselect_b32 s5, s10, s16
	s_cselect_b32 s10, s17, s18
	s_cmp_eq_u32 s4, 0
	s_cselect_b32 s79, s5, s7
	s_cselect_b32 s80, s10, s6
	s_lshr_b32 s98, s2, 3
	s_and_b32 s98, s98, 7
	s_lshr_b32 s98, 0x54, s98
	s_bitcmp1_b32 s98, 0
	s_cbranch_scc0 .Lnorev
	s_mov_b32 s98, s79
	s_mov_b32 s79, s80
	s_mov_b32 s80, s98
.Lnorev:
	v_mov_b32_e32 v223, 0
	s_mov_b64 s[16:17], 0x80
	s_mov_b64 s[18:19], 0x20000
	s_mov_b64 s[20:21], 0x40000
	s_mov_b64 s[22:23], 0x60000
	s_mov_b64 s[34:35], 0x20080
	s_mov_b64 s[36:37], 0x6080000
	s_mov_b64 s[38:39], 0x7040000
	s_mov_b64 s[40:41], 0x7040080
	s_mov_b32 s81, 0x41000000
	s_mov_b64 s[42:43], 0x60a0000
	s_mov_b64 s[44:45], 0x7060000
	s_mov_b64 s[46:47], 0x7060080
	s_mov_b64 s[48:49], 0x6060000
	s_mov_b64 s[50:51], 0x7020000
	s_mov_b64 s[52:53], 0x7020080
	s_mov_b32 s82, 0xb000000
	v_mov_b32_e32 v232, 0xff800000
	s_lshr_b32 s83, s32, 8
	v_mov_b32_e32 v178, v254
	s_branch .LBB0_388

.LBB0_486:
	v_mov_b32_e32 v1, s6
	v_add_co_u32_e32 v2, vcc, 0x2940000, v1
	v_mov_b32_e32 v1, s7
	s_nop 0
	v_addc_co_u32_e32 v3, vcc, 0, v1, vcc
	flat_load_dwordx4 v[2:5], v[2:3]
	s_and_b32 s4, s21, -4
	s_or_b32 s11, s4, s22
	s_lshl_b32 s4, s11, 3
	s_add_i32 s10, s4, s28
	s_cmpk_gt_i32 s10, 0x7ff
	s_mov_b32 s4, 0x2940000
	s_bitcmp1_b32 s20, 2
	s_cbranch_scc1 .LBB0_489
	s_cmpk_gt_i32 s10, 0x7ff
	s_cbranch_scc1 .LBB0_489
	v_mov_b32_e32 v1, s6
	v_add_co_u32_e32 v6, vcc, s4, v1
	v_mov_b32_e32 v1, s7
	s_nop 0
	v_addc_co_u32_e32 v7, vcc, 0, v1, vcc
	flat_load_dwordx2 v[8:9], v[6:7] offset:16
	s_lshl_b32 s8, s28, 14
	v_and_b32_e32 v1, 7, v0
	v_lshrrev_b32_e32 v10, 3, v178
	s_add_i32 s8, s8, 0
	v_lshlrev_b32_e32 v26, 4, v1
	v_mov_b32_e32 v27, 0
	v_mul_u32_u24_e32 v12, 0x84, v10
	v_mul_u32_u24_e32 v1, 0x420, v1
	v_lshlrev_b32_e32 v6, 2, v10
	v_add_u32_e32 v13, s8, v26
	s_mov_b64 s[4:5], 0x1e00000
	v_add3_u32 v11, s8, v1, v6
	v_lshl_add_u64 v[6:7], s[6:7], 0, v[26:27]
	v_add_u32_e32 v12, v13, v12
	s_lshl_b32 s12, s10, 5
	v_lshl_add_u64 v[6:7], v[6:7], 0, s[4:5]
	v_add_u32_e32 v13, 0x420, v12
	v_add_u32_e32 v14, 0x428, v12
	v_add_u32_e32 v15, 0x840, v12
	v_add_u32_e32 v16, 0x848, v12
	v_add_u32_e32 v17, 0xc60, v12
	v_add_u32_e32 v18, 0xc68, v12
	v_add_u32_e32 v19, 0x1080, v12
	v_add_u32_e32 v20, 0x1088, v12
	v_add_u32_e32 v21, 0x14a0, v12
	v_add_u32_e32 v22, 0x14a8, v12
	v_add_u32_e32 v23, 0x18c0, v12
	v_add_u32_e32 v24, 0x18c8, v12
	v_add_u32_e32 v25, 0x1ce0, v12
	s_waitcnt vmcnt(0) lgkmcnt(0)
	v_lshl_add_u64 v[8:9], v[8:9], 0, v[26:27]
	v_add_u32_e32 v26, 0x1ce8, v12

.LBB0_489:
	s_bitcmp0_b32 s20, 2
	s_cbranch_scc0 .Lslk_b
	s_waitcnt vmcnt(0) lgkmcnt(0)
	s_barrier
	s_branch .LBB0_493

.LBB0_508:
	s_barrier
	s_and_b32 s20, s2, 7
	s_lshl_b32 s20, s20, 5
	s_lshr_b32 s21, s2, 3
	s_add_i32 s20, s20, s21
	s_ashr_i32 s21, s20, 1
	v_and_b32_e32 v178, 63, v0
	s_branch .LBB0_486
